# mixer-A bias staged into LDS by DMA, bias wait is lgkmcnt instead of vmcnt(0) so MIX stores stay in flight
# speedup vs baseline: 1.0108x; 1.0025x over previous
.LBB0_321:
	s_lshl_b32 s32, s77, 2
	s_add_i32 s32, s32, 0x20100
	v_add_u32_e32 v116, s87, v200
	v_add_u32_e32 v116, s77, v116
	v_lshlrev_b32_e32 v116, 2, v116
	s_mov_b32 m0, s32
	s_nop 0
	global_load_lds_dword v116, s[56:57]
	v_add_u32_e32 v112, s87, v239
	v_ashrrev_i32_e32 v113, 31, v112
	v_lshlrev_b64 v[112:113], 8, v[112:113]
	v_lshl_add_u64 v[112:113], v[218:219], 0, v[112:113]
	s_mov_b32 m0, s97
	s_nop 0
	global_load_lds_dwordx4 v[112:113], off
	v_readlane_b32 s8, v254, 20
	v_readlane_b32 s9, v254, 21
	v_add_u32_e32 v114, s97, v212
	s_andn2_b64 vcc, exec, s[8:9]
	s_cbranch_vccnz .LBB0_323
	s_add_i32 m0, s97, 0x3c0
	s_nop 0
	global_load_lds_dwordx4 v[112:113], off offset:64

.LBB0_338:
	v_add_u32_e32 v128, s87, v234
	v_ashrrev_i32_e32 v129, 31, v128
	v_lshl_add_u64 v[168:169], v[128:129], 2, s[56:57]
	v_lshl_add_u32 v130, v233, 2, s32
	ds_read_b32 v130, v130
	v_lshlrev_b32_e32 v131, 16, v127
	v_and_b32_e32 v127, 0xffff0000, v127
	v_lshlrev_b32_e32 v132, 16, v126
	v_and_b32_e32 v126, 0xffff0000, v126
	v_lshlrev_b32_e32 v133, 16, v125
	v_and_b32_e32 v125, 0xffff0000, v125
	v_lshlrev_b32_e32 v134, 16, v124
	v_and_b32_e32 v124, 0xffff0000, v124
	v_add_u32_e32 v171, s99, v212
	v_add_u32_e32 v128, s94, v234
	v_ashrrev_i32_e32 v129, 31, v128
	s_and_b64 vcc, exec, s[8:9]
	s_waitcnt vmcnt(0) lgkmcnt(0)
	v_fma_f32 v64, v116, v64, v130
	v_fma_f32 v65, v117, v65, v130
	v_fma_f32 v66, v118, v66, v130
	v_fma_f32 v67, v119, v67, v130
	v_fma_f32 v68, v112, v68, v130
	v_fma_f32 v69, v113, v69, v130
	v_fma_f32 v70, v114, v70, v130
	v_fmac_f32_e32 v130, v115, v71
	v_mul_f32_e32 v64, v64, v131
	v_mul_f32_e32 v65, v65, v127
	v_mul_f32_e32 v66, v66, v132
	v_mul_f32_e32 v67, v67, v126
	v_mul_f32_e32 v68, v68, v133
	v_mul_f32_e32 v69, v69, v125
	v_mul_f32_e32 v70, v70, v134
	v_mul_f32_e32 v71, v130, v124
	v_cvt_pk_bf16_f32 v64, v64, v65
	v_cvt_pk_bf16_f32 v65, v66, v67
	v_cvt_pk_bf16_f32 v66, v68, v69
	v_cvt_pk_bf16_f32 v67, v70, v71
	ds_read_b128 v[68:71], v171 offset:256
	v_lshlrev_b64 v[124:125], 12, v[128:129]
	v_lshl_add_u64 v[124:125], s[12:13], 0, v[124:125]
	v_lshl_add_u64 v[124:125], v[228:229], 1, v[124:125]
	global_store_dwordx4 v[124:125], v[64:67], off
	s_waitcnt lgkmcnt(0)
	s_nop 0
	v_lshlrev_b32_e32 v64, 16, v68
	v_and_b32_e32 v65, 0xffff0000, v68
	v_lshlrev_b32_e32 v66, 16, v69
	v_and_b32_e32 v67, 0xffff0000, v69
	v_lshlrev_b32_e32 v68, 16, v70
	v_and_b32_e32 v69, 0xffff0000, v70
	v_lshlrev_b32_e32 v70, 16, v71
	v_and_b32_e32 v71, 0xffff0000, v71
	v_mul_f32_e32 v64, v88, v64
	v_mul_f32_e32 v65, v90, v65
	v_mul_f32_e32 v66, v92, v66
	v_mul_f32_e32 v67, v94, v67
	v_mul_f32_e32 v68, v87, v68
	v_mul_f32_e32 v69, v89, v69
	v_mul_f32_e32 v70, v91, v70
	v_mul_f32_e32 v71, v93, v71
	v_cvt_pk_bf16_f32 v64, v64, v65
	v_cvt_pk_bf16_f32 v65, v66, v67
	v_cvt_pk_bf16_f32 v66, v68, v69
	v_cvt_pk_bf16_f32 v67, v70, v71
	s_nop 0
	v_mfma_f32_16x16x32_bf16 v[68:71], v[164:167], v[64:67], 0
	v_mfma_f32_16x16x32_bf16 v[64:67], v[160:163], v[64:67], 0
	s_cbranch_vccz .LBB0_353
	s_and_b64 vcc, exec, s[8:9]
	s_cbranch_vccz .LBB0_354

.LBB0_342:
	v_lshl_add_u32 v125, v233, 2, s32
	ds_read_b32 v125, v125 offset:64
	v_lshlrev_b32_e32 v126, 16, v123
	v_and_b32_e32 v123, 0xffff0000, v123
	v_add_u32_e32 v124, s94, v240
	v_add_u32_e32 v170, s43, v212
	s_and_b64 vcc, exec, s[8:9]
	s_waitcnt lgkmcnt(0)
	v_fma_f32 v68, v116, v68, v125
	v_fma_f32 v69, v117, v69, v125
	v_mul_f32_e32 v68, v68, v126
	v_mul_f32_e32 v69, v69, v123
	v_cvt_pk_bf16_f32 v68, v68, v69
	v_lshlrev_b32_e32 v69, 16, v122
	v_fma_f32 v70, v118, v70, v125
	v_mul_f32_e32 v69, v70, v69
	v_and_b32_e32 v70, 0xffff0000, v122
	v_fma_f32 v71, v119, v71, v125
	v_mul_f32_e32 v70, v71, v70
	v_cvt_pk_bf16_f32 v69, v69, v70
	v_lshlrev_b32_e32 v70, 16, v121
	v_fma_f32 v64, v112, v64, v125
	v_mul_f32_e32 v64, v64, v70
	v_and_b32_e32 v70, 0xffff0000, v121
	v_fma_f32 v65, v113, v65, v125
	v_mul_f32_e32 v65, v65, v70
	v_cvt_pk_bf16_f32 v70, v64, v65
	v_lshlrev_b32_e32 v64, 16, v120
	v_fma_f32 v65, v114, v66, v125
	v_mul_f32_e32 v64, v65, v64
	v_and_b32_e32 v65, 0xffff0000, v120
	v_fmac_f32_e32 v125, v115, v67
	v_mul_f32_e32 v65, v125, v65
	v_ashrrev_i32_e32 v125, 31, v124
	v_cvt_pk_bf16_f32 v71, v64, v65
	v_lshlrev_b64 v[64:65], 12, v[124:125]
	v_lshl_add_u64 v[64:65], s[12:13], 0, v[64:65]
	v_lshl_add_u64 v[64:65], v[228:229], 1, v[64:65]
	global_store_dwordx4 v[64:65], v[68:71], off
	ds_read_b128 v[64:67], v170
	s_waitcnt lgkmcnt(0)
	v_lshlrev_b32_e32 v68, 16, v64
	v_and_b32_e32 v64, 0xffff0000, v64
	v_mul_f32_e32 v68, v88, v68
	v_mul_f32_e32 v64, v90, v64
	v_cvt_pk_bf16_f32 v64, v68, v64
	v_lshlrev_b32_e32 v68, 16, v65
	v_and_b32_e32 v65, 0xffff0000, v65
	v_mul_f32_e32 v68, v92, v68
	v_mul_f32_e32 v65, v94, v65
	v_cvt_pk_bf16_f32 v65, v68, v65
	v_lshlrev_b32_e32 v68, 16, v66
	v_and_b32_e32 v66, 0xffff0000, v66
	v_mul_f32_e32 v68, v87, v68
	v_mul_f32_e32 v66, v89, v66
	v_cvt_pk_bf16_f32 v66, v68, v66
	v_lshlrev_b32_e32 v68, 16, v67
	v_and_b32_e32 v67, 0xffff0000, v67
	v_mul_f32_e32 v67, v93, v67
	v_mul_f32_e32 v68, v91, v68
	v_cvt_pk_bf16_f32 v67, v68, v67
	ds_read_b128 v[120:123], v170 offset:1024
	v_mfma_f32_16x16x32_bf16 v[68:71], v[164:167], v[64:67], 0
	s_waitcnt lgkmcnt(0)
	v_lshlrev_b32_e32 v124, 16, v120
	v_and_b32_e32 v120, 0xffff0000, v120
	v_mul_f32_e32 v124, v77, v124
	v_mul_f32_e32 v120, v79, v120
	v_cvt_pk_bf16_f32 v120, v124, v120
	v_lshlrev_b32_e32 v124, 16, v121
	v_and_b32_e32 v121, 0xffff0000, v121
	v_mul_f32_e32 v124, v84, v124
	v_mul_f32_e32 v121, v86, v121
	v_mfma_f32_16x16x32_bf16 v[64:67], v[160:163], v[64:67], 0
	v_cvt_pk_bf16_f32 v121, v124, v121
	v_lshlrev_b32_e32 v124, 16, v122
	v_and_b32_e32 v122, 0xffff0000, v122
	v_mul_f32_e32 v124, v76, v124
	v_mul_f32_e32 v122, v78, v122
	v_cvt_pk_bf16_f32 v122, v124, v122
	v_lshlrev_b32_e32 v124, 16, v123
	v_and_b32_e32 v123, 0xffff0000, v123
	v_mul_f32_e32 v123, v95, v123
	v_mul_f32_e32 v124, v85, v124
	v_cvt_pk_bf16_f32 v123, v124, v123
	s_nop 0
	v_mfma_f32_16x16x32_bf16 v[68:71], v[148:151], v[120:123], v[68:71]
	v_mfma_f32_16x16x32_bf16 v[64:67], v[144:147], v[120:123], v[64:67]
	s_cbranch_vccnz .LBB0_344
	ds_read_b128 v[120:123], v170 offset:2048
	s_waitcnt lgkmcnt(0)
	v_lshlrev_b32_e32 v124, 16, v120
	v_and_b32_e32 v120, 0xffff0000, v120
	v_mul_f32_e32 v124, v103, v124
	v_mul_f32_e32 v120, v102, v120
	v_cvt_pk_bf16_f32 v120, v124, v120
	v_lshlrev_b32_e32 v124, 16, v121
	v_and_b32_e32 v121, 0xffff0000, v121
	v_mul_f32_e32 v124, v101, v124
	v_mul_f32_e32 v121, v100, v121
	v_cvt_pk_bf16_f32 v121, v124, v121
	v_lshlrev_b32_e32 v124, 16, v122
	v_and_b32_e32 v122, 0xffff0000, v122
	v_mul_f32_e32 v124, v96, v124
	v_mul_f32_e32 v122, v97, v122
	v_cvt_pk_bf16_f32 v122, v124, v122
	v_lshlrev_b32_e32 v124, 16, v123
	v_and_b32_e32 v123, 0xffff0000, v123
	v_mul_f32_e32 v123, v99, v123
	v_mul_f32_e32 v124, v98, v124
	v_cvt_pk_bf16_f32 v123, v124, v123
	s_nop 0
	v_mfma_f32_16x16x32_bf16 v[68:71], v[140:143], v[120:123], v[68:71]
	v_mfma_f32_16x16x32_bf16 v[64:67], v[136:139], v[120:123], v[64:67]

.LBB0_346:
	v_lshl_add_u32 v122, v233, 2, s32
	ds_read_b32 v122, v122 offset:128
	v_lshlrev_b32_e32 v123, 16, v83
	v_and_b32_e32 v83, 0xffff0000, v83
	v_lshlrev_b32_e32 v124, 16, v82
	v_and_b32_e32 v82, 0xffff0000, v82
	v_lshlrev_b32_e32 v125, 16, v81
	v_and_b32_e32 v81, 0xffff0000, v81
	v_lshlrev_b32_e32 v126, 16, v80
	v_and_b32_e32 v80, 0xffff0000, v80
	v_add_u32_e32 v172, s75, v212
	v_add_u32_e32 v120, s94, v241
	v_ashrrev_i32_e32 v121, 31, v120
	s_and_b64 vcc, exec, s[8:9]
	s_waitcnt lgkmcnt(0)
	v_fma_f32 v68, v116, v68, v122
	v_fma_f32 v69, v117, v69, v122
	v_fma_f32 v70, v118, v70, v122
	v_fma_f32 v71, v119, v71, v122
	v_fma_f32 v64, v112, v64, v122
	v_fma_f32 v65, v113, v65, v122
	v_fma_f32 v66, v114, v66, v122
	v_fmac_f32_e32 v122, v115, v67
	v_mul_f32_e32 v67, v68, v123
	v_mul_f32_e32 v68, v69, v83
	v_mul_f32_e32 v69, v70, v124
	v_mul_f32_e32 v70, v71, v82
	v_mul_f32_e32 v71, v64, v125
	v_mul_f32_e32 v81, v65, v81
	v_mul_f32_e32 v82, v66, v126
	v_mul_f32_e32 v80, v122, v80
	v_cvt_pk_bf16_f32 v64, v67, v68
	v_cvt_pk_bf16_f32 v65, v69, v70
	v_cvt_pk_bf16_f32 v66, v71, v81
	v_cvt_pk_bf16_f32 v67, v82, v80
	ds_read_b128 v[68:71], v172 offset:256
	v_lshlrev_b64 v[80:81], 12, v[120:121]
	v_lshl_add_u64 v[80:81], s[12:13], 0, v[80:81]
	v_lshl_add_u64 v[80:81], v[228:229], 1, v[80:81]
	global_store_dwordx4 v[80:81], v[64:67], off
	s_waitcnt lgkmcnt(0)
	s_nop 0
	v_lshlrev_b32_e32 v64, 16, v68
	v_and_b32_e32 v65, 0xffff0000, v68
	v_lshlrev_b32_e32 v66, 16, v69
	v_and_b32_e32 v67, 0xffff0000, v69
	v_lshlrev_b32_e32 v68, 16, v70
	v_and_b32_e32 v69, 0xffff0000, v70
	v_lshlrev_b32_e32 v70, 16, v71
	v_and_b32_e32 v71, 0xffff0000, v71
	v_mul_f32_e32 v64, v88, v64
	v_mul_f32_e32 v65, v90, v65
	v_mul_f32_e32 v66, v92, v66
	v_mul_f32_e32 v67, v94, v67
	v_mul_f32_e32 v68, v87, v68
	v_mul_f32_e32 v69, v89, v69
	v_mul_f32_e32 v70, v91, v70
	v_mul_f32_e32 v71, v93, v71
	v_cvt_pk_bf16_f32 v64, v64, v65
	v_cvt_pk_bf16_f32 v65, v66, v67
	v_cvt_pk_bf16_f32 v66, v68, v69
	v_cvt_pk_bf16_f32 v67, v70, v71
	ds_read_b128 v[80:83], v172 offset:1280
	v_mfma_f32_16x16x32_bf16 v[68:71], v[164:167], v[64:67], 0
	s_waitcnt lgkmcnt(0)
	v_lshlrev_b32_e32 v87, 16, v80
	v_mfma_f32_16x16x32_bf16 v[64:67], v[160:163], v[64:67], 0
	v_and_b32_e32 v80, 0xffff0000, v80
	v_lshlrev_b32_e32 v89, 16, v82
	v_and_b32_e32 v82, 0xffff0000, v82
	v_lshlrev_b32_e32 v88, 16, v81
	v_and_b32_e32 v81, 0xffff0000, v81
	v_lshlrev_b32_e32 v90, 16, v83
	v_and_b32_e32 v83, 0xffff0000, v83
	v_mul_f32_e32 v77, v77, v87
	v_mul_f32_e32 v79, v79, v80
	v_mul_f32_e32 v78, v78, v82
	v_mul_f32_e32 v80, v84, v88
	v_mul_f32_e32 v81, v86, v81
	v_mul_f32_e32 v84, v76, v89
	v_mul_f32_e32 v82, v85, v90
	v_mul_f32_e32 v83, v95, v83
	v_cvt_pk_bf16_f32 v76, v77, v79
	v_cvt_pk_bf16_f32 v77, v80, v81
	v_cvt_pk_bf16_f32 v78, v84, v78
	v_cvt_pk_bf16_f32 v79, v82, v83
	s_nop 0
	v_mfma_f32_16x16x32_bf16 v[68:71], v[148:151], v[76:79], v[68:71]
	v_mfma_f32_16x16x32_bf16 v[64:67], v[144:147], v[76:79], v[64:67]
	s_cbranch_vccnz .LBB0_348
	ds_read_b128 v[76:79], v172 offset:2304
	s_waitcnt lgkmcnt(0)
	v_lshlrev_b32_e32 v80, 16, v76
	v_and_b32_e32 v76, 0xffff0000, v76
	v_mul_f32_e32 v80, v103, v80
	v_mul_f32_e32 v76, v102, v76
	v_cvt_pk_bf16_f32 v76, v80, v76
	v_lshlrev_b32_e32 v80, 16, v77
	v_and_b32_e32 v77, 0xffff0000, v77
	v_mul_f32_e32 v80, v101, v80
	v_mul_f32_e32 v77, v100, v77
	v_cvt_pk_bf16_f32 v77, v80, v77
	v_lshlrev_b32_e32 v80, 16, v78
	v_and_b32_e32 v78, 0xffff0000, v78
	v_mul_f32_e32 v80, v96, v80
	v_mul_f32_e32 v78, v97, v78
	v_cvt_pk_bf16_f32 v78, v80, v78
	v_lshlrev_b32_e32 v80, 16, v79
	v_and_b32_e32 v79, 0xffff0000, v79
	v_mul_f32_e32 v79, v99, v79
	v_mul_f32_e32 v80, v98, v80
	v_cvt_pk_bf16_f32 v79, v80, v79
	s_nop 0
	v_mfma_f32_16x16x32_bf16 v[68:71], v[140:143], v[76:79], v[68:71]
	v_mfma_f32_16x16x32_bf16 v[64:67], v[136:139], v[76:79], v[64:67]

.LBB0_350:
	v_lshl_add_u32 v77, v233, 2, s32
	ds_read_b32 v77, v77 offset:192
	v_lshlrev_b32_e32 v78, 16, v75
	v_and_b32_e32 v75, 0xffff0000, v75
	v_add_u32_e32 v76, s94, v242
	s_or_b32 s16, s72, 1
	s_ashr_i32 s17, s16, 31
	s_lshl_b32 s26, s16, 7
	s_lshl_b64 s[16:17], s[16:17], 18
	s_ashr_i32 s27, s26, 31
	v_lshl_add_u64 v[88:89], s[26:27], 2, v[214:215]
	v_mov_b32_e32 v96, 0
	s_waitcnt lgkmcnt(0)
	v_fma_f32 v68, v116, v68, v77
	v_fma_f32 v69, v117, v69, v77
	v_mul_f32_e32 v68, v68, v78
	v_mul_f32_e32 v69, v69, v75
	v_cvt_pk_bf16_f32 v68, v68, v69
	v_lshlrev_b32_e32 v69, 16, v74
	v_fma_f32 v70, v118, v70, v77
	v_mul_f32_e32 v69, v70, v69
	v_and_b32_e32 v70, 0xffff0000, v74
	v_fma_f32 v71, v119, v71, v77
	v_mul_f32_e32 v70, v71, v70
	v_cvt_pk_bf16_f32 v69, v69, v70
	v_lshlrev_b32_e32 v70, 16, v73
	v_fma_f32 v64, v112, v64, v77
	v_mul_f32_e32 v64, v64, v70
	v_and_b32_e32 v70, 0xffff0000, v73
	v_fma_f32 v65, v113, v65, v77
	v_mul_f32_e32 v65, v65, v70
	v_cvt_pk_bf16_f32 v70, v64, v65
	v_lshlrev_b32_e32 v64, 16, v72
	v_fma_f32 v65, v114, v66, v77
	v_mul_f32_e32 v64, v65, v64
	v_and_b32_e32 v65, 0xffff0000, v72
	v_fmac_f32_e32 v77, v115, v67
	v_mul_f32_e32 v65, v77, v65
	v_ashrrev_i32_e32 v77, 31, v76
	v_cvt_pk_bf16_f32 v71, v64, v65
	v_lshlrev_b64 v[64:65], 12, v[76:77]
	v_lshl_add_u64 v[64:65], s[12:13], 0, v[64:65]
	v_lshl_add_u64 v[64:65], v[228:229], 1, v[64:65]
	global_store_dwordx4 v[64:65], v[68:71], off
	v_lshl_add_u64 v[64:65], v[216:217], 0, s[16:17]
	v_lshl_add_u64 v[90:91], v[64:65], 0, s[40:41]
	v_add_co_u32_e32 v72, vcc, 0x1000, v90
	global_load_dwordx4 v[100:103], v[88:89], off offset:16
	global_load_dwordx4 v[104:107], v[88:89], off
	v_addc_co_u32_e32 v73, vcc, 0, v91, vcc
	global_load_dwordx4 v[64:67], v[90:91], off nt
	global_load_dwordx4 v[68:71], v[72:73], off nt
	global_load_dwordx4 v[128:131], v[88:89], off offset:144
	global_load_dwordx4 v[132:135], v[88:89], off offset:128
	global_load_dwordx4 v[80:83], v[90:91], off offset:1024 nt
	global_load_dwordx4 v[84:87], v[72:73], off offset:1024 nt
	s_and_b64 vcc, exec, s[8:9]
	s_cbranch_vccnz .LBB0_355
	v_add_co_u32_e32 v72, vcc, 0x1000, v90
	global_load_dwordx4 v[108:111], v[88:89], off offset:256
	global_load_dwordx4 v[124:127], v[88:89], off offset:272
	v_addc_co_u32_e32 v73, vcc, 0, v91, vcc
	global_load_dwordx4 v[76:79], v[90:91], off offset:2048 nt
	s_nop 0
	global_load_dwordx4 v[72:75], v[72:73], off offset:2048 nt
	s_and_b64 vcc, exec, s[8:9]
	s_cbranch_vccz .LBB0_356

.LBB0_363:
	v_lshl_add_u32 v56, v233, 2, s32
	ds_read_b32 v56, v56
	v_lshlrev_b32_e32 v57, 16, v55
	v_and_b32_e32 v55, 0xffff0000, v55
	v_lshlrev_b32_e32 v58, 16, v54
	v_and_b32_e32 v54, 0xffff0000, v54
	v_lshlrev_b32_e32 v59, 16, v53
	v_and_b32_e32 v60, 0xffff0000, v53
	v_lshlrev_b32_e32 v61, 16, v52
	v_and_b32_e32 v62, 0xffff0000, v52
	s_or_b32 s40, s94, 0x80
	v_add_u32_e32 v52, s40, v234
	v_ashrrev_i32_e32 v53, 31, v52
	v_lshlrev_b64 v[52:53], 12, v[52:53]
	v_lshl_add_u64 v[52:53], s[12:13], 0, v[52:53]
	v_lshl_add_u64 v[52:53], v[228:229], 1, v[52:53]
	s_and_b64 vcc, exec, s[8:9]
	s_waitcnt vmcnt(0) lgkmcnt(0)
	v_fma_f32 v0, v116, v0, v56
	v_fma_f32 v1, v117, v1, v56
	v_fma_f32 v2, v118, v2, v56
	v_fma_f32 v3, v119, v3, v56
	v_fma_f32 v4, v112, v4, v56
	v_fma_f32 v5, v113, v5, v56
	v_fma_f32 v6, v114, v6, v56
	v_fmac_f32_e32 v56, v115, v7
	v_mul_f32_e32 v0, v0, v57
	v_mul_f32_e32 v1, v1, v55
	v_mul_f32_e32 v2, v2, v58
	v_mul_f32_e32 v3, v3, v54
	v_mul_f32_e32 v4, v4, v59
	v_mul_f32_e32 v5, v5, v60
	v_mul_f32_e32 v6, v6, v61
	v_mul_f32_e32 v7, v56, v62
	v_cvt_pk_bf16_f32 v0, v0, v1
	v_cvt_pk_bf16_f32 v1, v2, v3
	v_cvt_pk_bf16_f32 v2, v4, v5
	v_cvt_pk_bf16_f32 v3, v6, v7
	ds_read_b128 v[4:7], v171 offset:256
	global_store_dwordx4 v[52:53], v[0:3], off
	s_waitcnt lgkmcnt(0)
	s_nop 0
	v_lshlrev_b32_e32 v0, 16, v4
	v_and_b32_e32 v1, 0xffff0000, v4
	v_lshlrev_b32_e32 v2, 16, v5
	v_and_b32_e32 v3, 0xffff0000, v5
	v_lshlrev_b32_e32 v4, 16, v6
	v_and_b32_e32 v5, 0xffff0000, v6
	v_lshlrev_b32_e32 v6, 16, v7
	v_and_b32_e32 v7, 0xffff0000, v7
	v_mul_f32_e32 v0, v24, v0
	v_mul_f32_e32 v1, v26, v1
	v_mul_f32_e32 v2, v28, v2
	v_mul_f32_e32 v3, v30, v3
	v_mul_f32_e32 v4, v23, v4
	v_mul_f32_e32 v5, v25, v5
	v_mul_f32_e32 v6, v27, v6
	v_mul_f32_e32 v7, v29, v7
	v_cvt_pk_bf16_f32 v0, v0, v1
	v_cvt_pk_bf16_f32 v1, v2, v3
	v_cvt_pk_bf16_f32 v2, v4, v5
	v_cvt_pk_bf16_f32 v3, v6, v7
	s_nop 0
	v_mfma_f32_16x16x32_bf16 v[4:7], v[64:67], v[0:3], 0
	v_mfma_f32_16x16x32_bf16 v[0:3], v[68:71], v[0:3], 0
	s_cbranch_vccz .LBB0_378
	s_and_b64 vcc, exec, s[8:9]
	s_cbranch_vccz .LBB0_379

.LBB0_367:
	v_lshl_add_u32 v53, v233, 2, s32
	ds_read_b32 v53, v53 offset:64
	v_lshlrev_b32_e32 v54, 16, v51
	v_and_b32_e32 v51, 0xffff0000, v51
	v_add_u32_e32 v52, s40, v240
	s_and_b64 vcc, exec, s[8:9]
	s_waitcnt lgkmcnt(0)
	s_nop 0
	v_fma_f32 v4, v116, v4, v53
	v_fma_f32 v5, v117, v5, v53
	v_mul_f32_e32 v4, v4, v54
	v_mul_f32_e32 v5, v5, v51
	v_cvt_pk_bf16_f32 v4, v4, v5
	v_lshlrev_b32_e32 v5, 16, v50
	v_fma_f32 v6, v118, v6, v53
	v_mul_f32_e32 v5, v6, v5
	v_and_b32_e32 v6, 0xffff0000, v50
	v_fma_f32 v7, v119, v7, v53
	v_mul_f32_e32 v6, v7, v6
	v_cvt_pk_bf16_f32 v5, v5, v6
	v_lshlrev_b32_e32 v6, 16, v49
	v_fma_f32 v0, v112, v0, v53
	v_mul_f32_e32 v0, v0, v6
	v_and_b32_e32 v6, 0xffff0000, v49
	v_fma_f32 v1, v113, v1, v53
	v_mul_f32_e32 v1, v1, v6
	v_cvt_pk_bf16_f32 v6, v0, v1
	v_lshlrev_b32_e32 v0, 16, v48
	v_fma_f32 v1, v114, v2, v53
	v_mul_f32_e32 v0, v1, v0
	v_and_b32_e32 v1, 0xffff0000, v48
	v_fmac_f32_e32 v53, v115, v3
	v_mul_f32_e32 v1, v53, v1
	v_ashrrev_i32_e32 v53, 31, v52
	v_cvt_pk_bf16_f32 v7, v0, v1
	v_lshlrev_b64 v[0:1], 12, v[52:53]
	v_lshl_add_u64 v[0:1], s[12:13], 0, v[0:1]
	v_lshl_add_u64 v[0:1], v[228:229], 1, v[0:1]
	global_store_dwordx4 v[0:1], v[4:7], off
	ds_read_b128 v[0:3], v170
	s_waitcnt lgkmcnt(0)
	v_lshlrev_b32_e32 v4, 16, v0
	v_and_b32_e32 v0, 0xffff0000, v0
	v_mul_f32_e32 v4, v24, v4
	v_mul_f32_e32 v0, v26, v0
	v_cvt_pk_bf16_f32 v0, v4, v0
	v_lshlrev_b32_e32 v4, 16, v1
	v_and_b32_e32 v1, 0xffff0000, v1
	v_mul_f32_e32 v4, v28, v4
	v_mul_f32_e32 v1, v30, v1
	v_cvt_pk_bf16_f32 v1, v4, v1
	v_lshlrev_b32_e32 v4, 16, v2
	v_and_b32_e32 v2, 0xffff0000, v2
	v_mul_f32_e32 v4, v23, v4
	v_mul_f32_e32 v2, v25, v2
	v_cvt_pk_bf16_f32 v2, v4, v2
	v_lshlrev_b32_e32 v4, 16, v3
	v_and_b32_e32 v3, 0xffff0000, v3
	v_mul_f32_e32 v3, v29, v3
	v_mul_f32_e32 v4, v27, v4
	v_cvt_pk_bf16_f32 v3, v4, v3
	ds_read_b128 v[48:51], v170 offset:1024
	v_mfma_f32_16x16x32_bf16 v[4:7], v[64:67], v[0:3], 0
	s_waitcnt lgkmcnt(0)
	v_lshlrev_b32_e32 v52, 16, v48
	v_and_b32_e32 v48, 0xffff0000, v48
	v_mul_f32_e32 v52, v13, v52
	v_mul_f32_e32 v48, v15, v48
	v_cvt_pk_bf16_f32 v48, v52, v48
	v_lshlrev_b32_e32 v52, 16, v49
	v_and_b32_e32 v49, 0xffff0000, v49
	v_mul_f32_e32 v52, v20, v52
	v_mul_f32_e32 v49, v22, v49
	v_mfma_f32_16x16x32_bf16 v[0:3], v[68:71], v[0:3], 0
	v_cvt_pk_bf16_f32 v49, v52, v49
	v_lshlrev_b32_e32 v52, 16, v50
	v_and_b32_e32 v50, 0xffff0000, v50
	v_mul_f32_e32 v52, v12, v52
	v_mul_f32_e32 v50, v14, v50
	v_cvt_pk_bf16_f32 v50, v52, v50
	v_lshlrev_b32_e32 v52, 16, v51
	v_and_b32_e32 v51, 0xffff0000, v51
	v_mul_f32_e32 v51, v31, v51
	v_mul_f32_e32 v52, v21, v52
	v_cvt_pk_bf16_f32 v51, v52, v51
	s_nop 0
	v_mfma_f32_16x16x32_bf16 v[4:7], v[80:83], v[48:51], v[4:7]
	v_mfma_f32_16x16x32_bf16 v[0:3], v[84:87], v[48:51], v[0:3]
	s_cbranch_vccnz .LBB0_369
	ds_read_b128 v[48:51], v170 offset:2048
	s_waitcnt lgkmcnt(0)
	v_lshlrev_b32_e32 v52, 16, v48
	v_and_b32_e32 v48, 0xffff0000, v48
	v_mul_f32_e32 v52, v39, v52
	v_mul_f32_e32 v48, v38, v48
	v_cvt_pk_bf16_f32 v48, v52, v48
	v_lshlrev_b32_e32 v52, 16, v49
	v_and_b32_e32 v49, 0xffff0000, v49
	v_mul_f32_e32 v52, v37, v52
	v_mul_f32_e32 v49, v36, v49
	v_cvt_pk_bf16_f32 v49, v52, v49
	v_lshlrev_b32_e32 v52, 16, v50
	v_and_b32_e32 v50, 0xffff0000, v50
	v_mul_f32_e32 v52, v32, v52
	v_mul_f32_e32 v50, v33, v50
	v_cvt_pk_bf16_f32 v50, v52, v50
	v_lshlrev_b32_e32 v52, 16, v51
	v_and_b32_e32 v51, 0xffff0000, v51
	v_mul_f32_e32 v51, v35, v51
	v_mul_f32_e32 v52, v34, v52
	v_cvt_pk_bf16_f32 v51, v52, v51
	s_nop 0
	v_mfma_f32_16x16x32_bf16 v[4:7], v[76:79], v[48:51], v[4:7]
	v_mfma_f32_16x16x32_bf16 v[0:3], v[72:75], v[48:51], v[0:3]

.LBB0_371:
	v_lshl_add_u32 v50, v233, 2, s32
	ds_read_b32 v50, v50 offset:128
	v_lshlrev_b32_e32 v51, 16, v19
	v_and_b32_e32 v19, 0xffff0000, v19
	v_lshlrev_b32_e32 v52, 16, v18
	v_and_b32_e32 v18, 0xffff0000, v18
	v_lshlrev_b32_e32 v53, 16, v17
	v_and_b32_e32 v17, 0xffff0000, v17
	v_lshlrev_b32_e32 v54, 16, v16
	v_and_b32_e32 v16, 0xffff0000, v16
	v_add_u32_e32 v48, s40, v241
	v_ashrrev_i32_e32 v49, 31, v48
	s_and_b64 vcc, exec, s[8:9]
	s_waitcnt lgkmcnt(0)
	v_fma_f32 v4, v116, v4, v50
	v_fma_f32 v5, v117, v5, v50
	v_fma_f32 v6, v118, v6, v50
	v_fma_f32 v7, v119, v7, v50
	v_fma_f32 v0, v112, v0, v50
	v_fma_f32 v1, v113, v1, v50
	v_fma_f32 v2, v114, v2, v50
	v_fmac_f32_e32 v50, v115, v3
	v_mul_f32_e32 v3, v4, v51
	v_mul_f32_e32 v4, v5, v19
	v_mul_f32_e32 v5, v6, v52
	v_mul_f32_e32 v6, v7, v18
	v_mul_f32_e32 v7, v0, v53
	v_mul_f32_e32 v17, v1, v17
	v_mul_f32_e32 v18, v2, v54
	v_mul_f32_e32 v16, v50, v16
	v_cvt_pk_bf16_f32 v0, v3, v4
	v_cvt_pk_bf16_f32 v1, v5, v6
	v_cvt_pk_bf16_f32 v2, v7, v17
	v_cvt_pk_bf16_f32 v3, v18, v16
	ds_read_b128 v[4:7], v172 offset:256
	v_lshlrev_b64 v[16:17], 12, v[48:49]
	v_lshl_add_u64 v[16:17], s[12:13], 0, v[16:17]
	v_lshl_add_u64 v[16:17], v[228:229], 1, v[16:17]
	global_store_dwordx4 v[16:17], v[0:3], off
	s_waitcnt lgkmcnt(0)
	s_nop 0
	v_lshlrev_b32_e32 v0, 16, v4
	v_and_b32_e32 v1, 0xffff0000, v4
	v_lshlrev_b32_e32 v2, 16, v5
	v_and_b32_e32 v3, 0xffff0000, v5
	v_lshlrev_b32_e32 v4, 16, v6
	v_and_b32_e32 v5, 0xffff0000, v6
	v_lshlrev_b32_e32 v6, 16, v7
	v_and_b32_e32 v7, 0xffff0000, v7
	v_mul_f32_e32 v0, v24, v0
	v_mul_f32_e32 v1, v26, v1
	v_mul_f32_e32 v2, v28, v2
	v_mul_f32_e32 v3, v30, v3
	v_mul_f32_e32 v4, v23, v4
	v_mul_f32_e32 v5, v25, v5
	v_mul_f32_e32 v6, v27, v6
	v_mul_f32_e32 v7, v29, v7
	v_cvt_pk_bf16_f32 v0, v0, v1
	v_cvt_pk_bf16_f32 v1, v2, v3
	v_cvt_pk_bf16_f32 v2, v4, v5
	v_cvt_pk_bf16_f32 v3, v6, v7
	ds_read_b128 v[16:19], v172 offset:1280
	v_mfma_f32_16x16x32_bf16 v[4:7], v[64:67], v[0:3], 0
	s_waitcnt lgkmcnt(0)
	v_lshlrev_b32_e32 v23, 16, v16
	v_mfma_f32_16x16x32_bf16 v[0:3], v[68:71], v[0:3], 0
	v_and_b32_e32 v16, 0xffff0000, v16
	v_lshlrev_b32_e32 v25, 16, v18
	v_and_b32_e32 v18, 0xffff0000, v18
	v_lshlrev_b32_e32 v24, 16, v17
	v_and_b32_e32 v17, 0xffff0000, v17
	v_lshlrev_b32_e32 v26, 16, v19
	v_and_b32_e32 v19, 0xffff0000, v19
	v_mul_f32_e32 v13, v13, v23
	v_mul_f32_e32 v15, v15, v16
	v_mul_f32_e32 v14, v14, v18
	v_mul_f32_e32 v16, v20, v24
	v_mul_f32_e32 v17, v22, v17
	v_mul_f32_e32 v20, v12, v25
	v_mul_f32_e32 v18, v21, v26
	v_mul_f32_e32 v19, v31, v19
	v_cvt_pk_bf16_f32 v12, v13, v15
	v_cvt_pk_bf16_f32 v13, v16, v17
	v_cvt_pk_bf16_f32 v14, v20, v14
	v_cvt_pk_bf16_f32 v15, v18, v19
	s_nop 0
	v_mfma_f32_16x16x32_bf16 v[4:7], v[80:83], v[12:15], v[4:7]
	v_mfma_f32_16x16x32_bf16 v[0:3], v[84:87], v[12:15], v[0:3]
	s_cbranch_vccnz .LBB0_373
	ds_read_b128 v[12:15], v172 offset:2304
	s_waitcnt lgkmcnt(0)
	v_lshlrev_b32_e32 v16, 16, v12
	v_and_b32_e32 v12, 0xffff0000, v12
	v_mul_f32_e32 v16, v39, v16
	v_mul_f32_e32 v12, v38, v12
	v_cvt_pk_bf16_f32 v12, v16, v12
	v_lshlrev_b32_e32 v16, 16, v13
	v_and_b32_e32 v13, 0xffff0000, v13
	v_mul_f32_e32 v16, v37, v16
	v_mul_f32_e32 v13, v36, v13
	v_cvt_pk_bf16_f32 v13, v16, v13
	v_lshlrev_b32_e32 v16, 16, v14
	v_and_b32_e32 v14, 0xffff0000, v14
	v_mul_f32_e32 v16, v32, v16
	v_mul_f32_e32 v14, v33, v14
	v_cvt_pk_bf16_f32 v14, v16, v14
	v_lshlrev_b32_e32 v16, 16, v15
	v_and_b32_e32 v15, 0xffff0000, v15
	v_mul_f32_e32 v15, v35, v15
	v_mul_f32_e32 v16, v34, v16
	v_cvt_pk_bf16_f32 v15, v16, v15
	s_nop 0
	v_mfma_f32_16x16x32_bf16 v[4:7], v[76:79], v[12:15], v[4:7]
	v_mfma_f32_16x16x32_bf16 v[0:3], v[72:75], v[12:15], v[0:3]

.LBB0_375:
	v_lshl_add_u32 v14, v233, 2, s32
	ds_read_b32 v14, v14 offset:192
	v_add_u32_e32 v12, s40, v242
	v_ashrrev_i32_e32 v13, 31, v12
	v_lshlrev_b32_e32 v15, 16, v11
	v_and_b32_e32 v11, 0xffff0000, v11
	v_lshlrev_b32_e32 v16, 16, v10
	v_lshlrev_b32_e32 v17, 16, v9
	v_and_b32_e32 v18, 0xffff0000, v9
	v_lshlrev_b32_e32 v19, 16, v8
	v_and_b32_e32 v20, 0xffff0000, v8
	v_lshlrev_b64 v[8:9], 12, v[12:13]
	v_and_b32_e32 v10, 0xffff0000, v10
	v_lshl_add_u64 v[8:9], s[12:13], 0, v[8:9]
	s_waitcnt lgkmcnt(0)
	v_fma_f32 v4, v116, v4, v14
	v_fma_f32 v5, v117, v5, v14
	v_fma_f32 v6, v118, v6, v14
	v_fma_f32 v7, v119, v7, v14
	v_fma_f32 v0, v112, v0, v14
	v_fma_f32 v1, v113, v1, v14
	v_fma_f32 v2, v114, v2, v14
	v_fmac_f32_e32 v14, v115, v3
	v_mul_f32_e32 v3, v4, v15
	v_mul_f32_e32 v4, v5, v11
	v_mul_f32_e32 v5, v6, v16
	v_mul_f32_e32 v6, v7, v10
	v_mul_f32_e32 v7, v0, v17
	v_mul_f32_e32 v10, v1, v18
	v_cvt_pk_bf16_f32 v0, v3, v4
	v_cvt_pk_bf16_f32 v1, v5, v6
	v_lshl_add_u64 v[4:5], v[228:229], 1, v[8:9]
	v_mul_f32_e32 v11, v2, v19
	v_mul_f32_e32 v12, v14, v20
	v_cvt_pk_bf16_f32 v2, v7, v10
	v_cvt_pk_bf16_f32 v3, v11, v12
	global_store_dwordx4 v[4:5], v[0:3], off
	s_andn2_b64 vcc, exec, s[6:7]
	s_mov_b64 s[6:7], -1
	s_cbranch_vccnz .LBB0_298
